# rstd row-scale loads of the in_proj/gate_up epilogues issued before the leading half's alignment barrier
# speedup vs baseline: 1.0070x; 1.0070x over previous
.LBB0_98:
	s_add_u32 s18, s44, 0xfffc0080
	s_addc_u32 s19, s45, -1
	s_add_i32 s46, 0, 0x10000
	s_cmp_eq_u32 s15, 12
	s_cselect_b32 s25, s7, s19
	s_cselect_b32 s24, s10, s18
	v_add_u32_e32 v148, s46, v150
	s_cselect_b32 s23, s5, s14
	s_cselect_b32 s22, s11, s13
	s_add_i32 s47, 0, 0x14000
	ds_read_b128 v[156:159], v148
	ds_read_b128 v[160:163], v148 offset:1024
	ds_read_b128 v[164:167], v148 offset:2048
	ds_read_b128 v[168:171], v148 offset:3072
	v_add_u32_e32 v148, s47, v150
	ds_read_b128 v[172:175], v148
	ds_read_b128 v[176:179], v148 offset:1024
	ds_read_b128 v[180:183], v148 offset:2048
	ds_read_b128 v[184:187], v148 offset:3072
	v_lshl_add_u64 v[148:149], s[44:45], 0, v[144:145]
	s_add_i32 m0, s29, 0xc000
	ds_read_b128 v[208:211], v155
	ds_read_b128 v[212:215], v155 offset:1024
	ds_read_b128 v[216:219], v155 offset:2048
	ds_read_b128 v[220:223], v155 offset:3072
	ds_read_b128 v[224:227], v155 offset:4096
	ds_read_b128 v[228:231], v155 offset:5120
	ds_read_b128 v[232:235], v155 offset:6144
	ds_read_b128 v[236:239], v155 offset:7168
	global_load_lds_dwordx4 v[148:149], off
	v_lshl_add_u64 v[148:149], s[44:45], 0, v[146:147]
	s_add_i32 m0, s29, 0xe000
	s_nop 0
	global_load_lds_dwordx4 v[148:149], off
	s_waitcnt vmcnt(8)
	s_waitcnt lgkmcnt(0)
	s_barrier
	s_setprio 1
	s_waitcnt lgkmcnt(0)
	v_mfma_f32_16x16x32_bf16 v[128:131], v[156:159], v[208:211], v[128:131]
	v_mfma_f32_16x16x32_bf16 v[120:123], v[164:167], v[208:211], v[120:123]
	v_mfma_f32_16x16x32_bf16 v[112:115], v[156:159], v[216:219], v[112:115]
	v_mfma_f32_16x16x32_bf16 v[104:107], v[164:167], v[216:219], v[104:107]
	v_mfma_f32_16x16x32_bf16 v[96:99], v[156:159], v[224:227], v[96:99]
	v_mfma_f32_16x16x32_bf16 v[88:91], v[164:167], v[224:227], v[88:91]
	v_mfma_f32_16x16x32_bf16 v[80:83], v[156:159], v[232:235], v[80:83]
	v_mfma_f32_16x16x32_bf16 v[72:75], v[164:167], v[232:235], v[72:75]
	v_mfma_f32_16x16x32_bf16 v[128:131], v[160:163], v[212:215], v[128:131]
	v_mfma_f32_16x16x32_bf16 v[120:123], v[168:171], v[212:215], v[120:123]
	v_mfma_f32_16x16x32_bf16 v[112:115], v[160:163], v[220:223], v[112:115]
	v_mfma_f32_16x16x32_bf16 v[104:107], v[168:171], v[220:223], v[104:107]
	v_mfma_f32_16x16x32_bf16 v[96:99], v[160:163], v[228:231], v[96:99]
	v_mfma_f32_16x16x32_bf16 v[88:91], v[168:171], v[228:231], v[88:91]
	v_mfma_f32_16x16x32_bf16 v[80:83], v[160:163], v[236:239], v[80:83]
	v_mfma_f32_16x16x32_bf16 v[72:75], v[168:171], v[236:239], v[72:75]
	s_setprio 0
	s_setprio 1
	v_mfma_f32_16x16x32_bf16 v[124:127], v[172:175], v[208:211], v[124:127]
	v_mfma_f32_16x16x32_bf16 v[116:119], v[180:183], v[208:211], v[116:119]
	v_mfma_f32_16x16x32_bf16 v[108:111], v[172:175], v[216:219], v[108:111]
	v_mfma_f32_16x16x32_bf16 v[100:103], v[180:183], v[216:219], v[100:103]
	v_mfma_f32_16x16x32_bf16 v[92:95], v[172:175], v[224:227], v[92:95]
	v_mfma_f32_16x16x32_bf16 v[84:87], v[180:183], v[224:227], v[84:87]
	v_mfma_f32_16x16x32_bf16 v[76:79], v[172:175], v[232:235], v[76:79]
	v_mfma_f32_16x16x32_bf16 v[68:71], v[180:183], v[232:235], v[68:71]
	v_mfma_f32_16x16x32_bf16 v[124:127], v[176:179], v[212:215], v[124:127]
	v_mfma_f32_16x16x32_bf16 v[116:119], v[184:187], v[212:215], v[116:119]
	v_mfma_f32_16x16x32_bf16 v[108:111], v[176:179], v[220:223], v[108:111]
	v_mfma_f32_16x16x32_bf16 v[100:103], v[184:187], v[220:223], v[100:103]
	v_mfma_f32_16x16x32_bf16 v[92:95], v[176:179], v[228:231], v[92:95]
	v_mfma_f32_16x16x32_bf16 v[84:87], v[184:187], v[228:231], v[84:87]
	v_mfma_f32_16x16x32_bf16 v[76:79], v[176:179], v[236:239], v[76:79]
	v_mfma_f32_16x16x32_bf16 v[68:71], v[184:187], v[236:239], v[68:71]
	s_setprio 0
	s_barrier
	s_add_i32 s18, s46, s28
	v_lshl_add_u64 v[148:149], s[22:23], 0, v[2:3]
	s_mov_b32 m0, s18
	ds_read_b128 v[208:211], v155 offset:16384
	ds_read_b128 v[212:215], v155 offset:17408
	ds_read_b128 v[216:219], v155 offset:18432
	ds_read_b128 v[220:223], v155 offset:19456
	ds_read_b128 v[224:227], v155 offset:20480
	ds_read_b128 v[228:231], v155 offset:21504
	ds_read_b128 v[232:235], v155 offset:22528
	ds_read_b128 v[236:239], v155 offset:23552
	global_load_lds_dwordx4 v[148:149], off
	s_add_i32 m0, s18, 0x2000
	s_add_u32 s18, s22, 0x40000
	v_lshl_add_u64 v[188:189], s[22:23], 0, v[142:143]
	s_addc_u32 s19, s23, 0
	s_add_i32 s46, s47, s28
	global_load_lds_dwordx4 v[188:189], off
	v_lshl_add_u64 v[196:197], s[18:19], 0, v[2:3]
	s_mov_b32 m0, s46
	v_lshl_add_u64 v[198:199], s[24:25], 0, v[140:141]
	global_load_lds_dwordx4 v[196:197], off
	v_lshl_add_u64 v[196:197], s[18:19], 0, v[142:143]
	s_add_i32 m0, s46, 0x2000
	s_nop 0
	global_load_lds_dwordx4 v[196:197], off
	v_lshl_add_u64 v[196:197], s[24:25], 0, v[0:1]
	s_mov_b32 m0, s29
	s_nop 0
	global_load_lds_dwordx4 v[196:197], off
	s_mov_b32 m0, s43
	s_nop 0
	global_load_lds_dwordx4 v[198:199], off
	s_waitcnt vmcnt(8)
	s_waitcnt lgkmcnt(0)
	s_barrier
	s_setprio 1
	s_waitcnt lgkmcnt(0)
	v_mfma_f32_16x16x32_bf16 v[64:67], v[156:159], v[208:211], v[64:67]
	v_mfma_f32_16x16x32_bf16 v[56:59], v[164:167], v[208:211], v[56:59]
	v_mfma_f32_16x16x32_bf16 v[48:51], v[156:159], v[216:219], v[48:51]
	v_mfma_f32_16x16x32_bf16 v[40:43], v[164:167], v[216:219], v[40:43]
	v_mfma_f32_16x16x32_bf16 v[32:35], v[156:159], v[224:227], v[32:35]
	v_mfma_f32_16x16x32_bf16 v[24:27], v[164:167], v[224:227], v[24:27]
	v_mfma_f32_16x16x32_bf16 v[16:19], v[156:159], v[232:235], v[16:19]
	v_mfma_f32_16x16x32_bf16 v[8:11], v[164:167], v[232:235], v[8:11]
	v_mfma_f32_16x16x32_bf16 v[64:67], v[160:163], v[212:215], v[64:67]
	v_mfma_f32_16x16x32_bf16 v[56:59], v[168:171], v[212:215], v[56:59]
	v_mfma_f32_16x16x32_bf16 v[48:51], v[160:163], v[220:223], v[48:51]
	v_mfma_f32_16x16x32_bf16 v[40:43], v[168:171], v[220:223], v[40:43]
	v_mfma_f32_16x16x32_bf16 v[32:35], v[160:163], v[228:231], v[32:35]
	v_mfma_f32_16x16x32_bf16 v[24:27], v[168:171], v[228:231], v[24:27]
	v_mfma_f32_16x16x32_bf16 v[16:19], v[160:163], v[236:239], v[16:19]
	v_mfma_f32_16x16x32_bf16 v[8:11], v[168:171], v[236:239], v[8:11]
	s_setprio 0
	s_setprio 1
	v_mfma_f32_16x16x32_bf16 v[60:63], v[172:175], v[208:211], v[60:63]
	v_mfma_f32_16x16x32_bf16 v[52:55], v[180:183], v[208:211], v[52:55]
	v_mfma_f32_16x16x32_bf16 v[44:47], v[172:175], v[216:219], v[44:47]
	v_mfma_f32_16x16x32_bf16 v[36:39], v[180:183], v[216:219], v[36:39]
	v_mfma_f32_16x16x32_bf16 v[28:31], v[172:175], v[224:227], v[28:31]
	v_mfma_f32_16x16x32_bf16 v[20:23], v[180:183], v[224:227], v[20:23]
	v_mfma_f32_16x16x32_bf16 v[12:15], v[172:175], v[232:235], v[12:15]
	v_mfma_f32_16x16x32_bf16 v[4:7], v[180:183], v[232:235], v[4:7]
	v_mfma_f32_16x16x32_bf16 v[60:63], v[176:179], v[212:215], v[60:63]
	v_mfma_f32_16x16x32_bf16 v[52:55], v[184:187], v[212:215], v[52:55]
	v_mfma_f32_16x16x32_bf16 v[44:47], v[176:179], v[220:223], v[44:47]
	v_mfma_f32_16x16x32_bf16 v[36:39], v[184:187], v[220:223], v[36:39]
	v_mfma_f32_16x16x32_bf16 v[28:31], v[176:179], v[228:231], v[28:31]
	v_mfma_f32_16x16x32_bf16 v[20:23], v[184:187], v[228:231], v[20:23]
	v_mfma_f32_16x16x32_bf16 v[12:15], v[176:179], v[236:239], v[12:15]
	v_mfma_f32_16x16x32_bf16 v[4:7], v[184:187], v[236:239], v[4:7]
	s_setprio 0
	s_barrier
	s_add_i32 s46, 0, 0x18000
	s_add_i32 s47, 0, 0x1c000
	v_add_u32_e32 v168, s46, v150
	v_add_u32_e32 v184, s47, v150
	ds_read_b128 v[156:159], v168
	ds_read_b128 v[160:163], v168 offset:1024
	ds_read_b128 v[164:167], v168 offset:2048
	ds_read_b128 v[168:171], v168 offset:3072
	ds_read_b128 v[172:175], v184
	ds_read_b128 v[176:179], v184 offset:1024
	ds_read_b128 v[180:183], v184 offset:2048
	ds_read_b128 v[184:187], v184 offset:3072
	s_add_u32 s18, s24, 0x40000
	s_addc_u32 s19, s25, 0
	s_mov_b32 m0, s48
	v_lshl_add_u64 v[200:201], s[18:19], 0, v[0:1]
	ds_read_b128 v[208:211], v155 offset:32768
	ds_read_b128 v[212:215], v155 offset:33792
	ds_read_b128 v[216:219], v155 offset:34816
	ds_read_b128 v[220:223], v155 offset:35840
	ds_read_b128 v[224:227], v155 offset:36864
	ds_read_b128 v[228:231], v155 offset:37888
	ds_read_b128 v[232:235], v155 offset:38912
	ds_read_b128 v[236:239], v155 offset:39936
	global_load_lds_dwordx4 v[200:201], off
	v_lshl_add_u64 v[200:201], s[18:19], 0, v[140:141]
	s_mov_b32 m0, s49
	s_nop 0
	global_load_lds_dwordx4 v[200:201], off
	s_waitcnt vmcnt(8)
	s_waitcnt lgkmcnt(0)
	s_barrier
	s_setprio 1
	s_waitcnt lgkmcnt(0)
	v_mfma_f32_16x16x32_bf16 v[128:131], v[156:159], v[208:211], v[128:131]
	v_mfma_f32_16x16x32_bf16 v[120:123], v[164:167], v[208:211], v[120:123]
	v_mfma_f32_16x16x32_bf16 v[112:115], v[156:159], v[216:219], v[112:115]
	v_mfma_f32_16x16x32_bf16 v[104:107], v[164:167], v[216:219], v[104:107]
	v_mfma_f32_16x16x32_bf16 v[96:99], v[156:159], v[224:227], v[96:99]
	v_mfma_f32_16x16x32_bf16 v[88:91], v[164:167], v[224:227], v[88:91]
	v_mfma_f32_16x16x32_bf16 v[80:83], v[156:159], v[232:235], v[80:83]
	v_mfma_f32_16x16x32_bf16 v[72:75], v[164:167], v[232:235], v[72:75]
	v_mfma_f32_16x16x32_bf16 v[128:131], v[160:163], v[212:215], v[128:131]
	v_mfma_f32_16x16x32_bf16 v[120:123], v[168:171], v[212:215], v[120:123]
	v_mfma_f32_16x16x32_bf16 v[112:115], v[160:163], v[220:223], v[112:115]
	v_mfma_f32_16x16x32_bf16 v[104:107], v[168:171], v[220:223], v[104:107]
	v_mfma_f32_16x16x32_bf16 v[96:99], v[160:163], v[228:231], v[96:99]
	v_mfma_f32_16x16x32_bf16 v[88:91], v[168:171], v[228:231], v[88:91]
	v_mfma_f32_16x16x32_bf16 v[80:83], v[160:163], v[236:239], v[80:83]
	v_mfma_f32_16x16x32_bf16 v[72:75], v[168:171], v[236:239], v[72:75]
	s_setprio 0
	s_setprio 1
	v_mfma_f32_16x16x32_bf16 v[124:127], v[172:175], v[208:211], v[124:127]
	v_mfma_f32_16x16x32_bf16 v[116:119], v[180:183], v[208:211], v[116:119]
	v_mfma_f32_16x16x32_bf16 v[108:111], v[172:175], v[216:219], v[108:111]
	v_mfma_f32_16x16x32_bf16 v[100:103], v[180:183], v[216:219], v[100:103]
	v_mfma_f32_16x16x32_bf16 v[92:95], v[172:175], v[224:227], v[92:95]
	v_mfma_f32_16x16x32_bf16 v[84:87], v[180:183], v[224:227], v[84:87]
	v_mfma_f32_16x16x32_bf16 v[76:79], v[172:175], v[232:235], v[76:79]
	v_mfma_f32_16x16x32_bf16 v[68:71], v[180:183], v[232:235], v[68:71]
	v_mfma_f32_16x16x32_bf16 v[124:127], v[176:179], v[212:215], v[124:127]
	v_mfma_f32_16x16x32_bf16 v[116:119], v[184:187], v[212:215], v[116:119]
	v_mfma_f32_16x16x32_bf16 v[108:111], v[176:179], v[220:223], v[108:111]
	v_mfma_f32_16x16x32_bf16 v[100:103], v[184:187], v[220:223], v[100:103]
	v_mfma_f32_16x16x32_bf16 v[92:95], v[176:179], v[228:231], v[92:95]
	v_mfma_f32_16x16x32_bf16 v[84:87], v[184:187], v[228:231], v[84:87]
	v_mfma_f32_16x16x32_bf16 v[76:79], v[176:179], v[236:239], v[76:79]
	v_mfma_f32_16x16x32_bf16 v[68:71], v[184:187], v[236:239], v[68:71]
	s_setprio 0
	s_barrier
	s_add_i32 s18, s46, s28
	v_lshl_add_u64 v[148:149], v[148:149], 0, s[92:93]
	s_mov_b32 m0, s18
	ds_read_b128 v[208:211], v155 offset:49152
	ds_read_b128 v[212:215], v155 offset:50176
	ds_read_b128 v[216:219], v155 offset:51200
	ds_read_b128 v[220:223], v155 offset:52224
	ds_read_b128 v[224:227], v155 offset:53248
	ds_read_b128 v[228:231], v155 offset:54272
	ds_read_b128 v[232:235], v155 offset:55296
	ds_read_b128 v[236:239], v155 offset:56320
	global_load_lds_dwordx4 v[148:149], off
	s_add_i32 m0, s18, 0x2000
	s_add_u32 s18, s22, 0x40080
	v_lshl_add_u64 v[148:149], v[188:189], 0, s[92:93]
	s_addc_u32 s19, s23, 0
	s_add_i32 s22, s47, s28
	global_load_lds_dwordx4 v[148:149], off
	v_lshl_add_u64 v[148:149], s[18:19], 0, v[2:3]
	s_mov_b32 m0, s22
	s_nop 0
	global_load_lds_dwordx4 v[148:149], off
	v_lshl_add_u64 v[148:149], s[18:19], 0, v[142:143]
	s_add_i32 m0, s22, 0x2000
	s_nop 0
	global_load_lds_dwordx4 v[148:149], off
	v_lshl_add_u64 v[148:149], v[196:197], 0, s[92:93]
	s_mov_b32 m0, s50
	s_nop 0
	global_load_lds_dwordx4 v[148:149], off
	v_lshl_add_u64 v[148:149], v[198:199], 0, s[92:93]
	s_mov_b32 m0, s51
	s_nop 0
	global_load_lds_dwordx4 v[148:149], off
	s_waitcnt vmcnt(8)
	s_waitcnt lgkmcnt(0)
	s_barrier
	s_setprio 1
	s_waitcnt lgkmcnt(0)
	v_mfma_f32_16x16x32_bf16 v[64:67], v[156:159], v[208:211], v[64:67]
	v_mfma_f32_16x16x32_bf16 v[56:59], v[164:167], v[208:211], v[56:59]
	v_mfma_f32_16x16x32_bf16 v[48:51], v[156:159], v[216:219], v[48:51]
	v_mfma_f32_16x16x32_bf16 v[40:43], v[164:167], v[216:219], v[40:43]
	v_mfma_f32_16x16x32_bf16 v[32:35], v[156:159], v[224:227], v[32:35]
	v_mfma_f32_16x16x32_bf16 v[24:27], v[164:167], v[224:227], v[24:27]
	v_mfma_f32_16x16x32_bf16 v[16:19], v[156:159], v[232:235], v[16:19]
	v_mfma_f32_16x16x32_bf16 v[8:11], v[164:167], v[232:235], v[8:11]
	v_mfma_f32_16x16x32_bf16 v[64:67], v[160:163], v[212:215], v[64:67]
	v_mfma_f32_16x16x32_bf16 v[56:59], v[168:171], v[212:215], v[56:59]
	v_mfma_f32_16x16x32_bf16 v[48:51], v[160:163], v[220:223], v[48:51]
	v_mfma_f32_16x16x32_bf16 v[40:43], v[168:171], v[220:223], v[40:43]
	v_mfma_f32_16x16x32_bf16 v[32:35], v[160:163], v[228:231], v[32:35]
	v_mfma_f32_16x16x32_bf16 v[24:27], v[168:171], v[228:231], v[24:27]
	v_mfma_f32_16x16x32_bf16 v[16:19], v[160:163], v[236:239], v[16:19]
	v_mfma_f32_16x16x32_bf16 v[8:11], v[168:171], v[236:239], v[8:11]
	s_setprio 0
	s_setprio 1
	v_mfma_f32_16x16x32_bf16 v[60:63], v[172:175], v[208:211], v[60:63]
	v_mfma_f32_16x16x32_bf16 v[52:55], v[180:183], v[208:211], v[52:55]
	v_mfma_f32_16x16x32_bf16 v[44:47], v[172:175], v[216:219], v[44:47]
	v_mfma_f32_16x16x32_bf16 v[36:39], v[180:183], v[216:219], v[36:39]
	v_mfma_f32_16x16x32_bf16 v[28:31], v[172:175], v[224:227], v[28:31]
	v_mfma_f32_16x16x32_bf16 v[20:23], v[180:183], v[224:227], v[20:23]
	v_mfma_f32_16x16x32_bf16 v[12:15], v[172:175], v[232:235], v[12:15]
	v_mfma_f32_16x16x32_bf16 v[4:7], v[180:183], v[232:235], v[4:7]
	v_mfma_f32_16x16x32_bf16 v[60:63], v[176:179], v[212:215], v[60:63]
	v_mfma_f32_16x16x32_bf16 v[52:55], v[184:187], v[212:215], v[52:55]
	v_mfma_f32_16x16x32_bf16 v[44:47], v[176:179], v[220:223], v[44:47]
	v_mfma_f32_16x16x32_bf16 v[36:39], v[184:187], v[220:223], v[36:39]
	v_mfma_f32_16x16x32_bf16 v[28:31], v[176:179], v[228:231], v[28:31]
	v_mfma_f32_16x16x32_bf16 v[20:23], v[184:187], v[228:231], v[20:23]
	v_mfma_f32_16x16x32_bf16 v[12:15], v[176:179], v[236:239], v[12:15]
	v_mfma_f32_16x16x32_bf16 v[4:7], v[184:187], v[236:239], v[4:7]
	s_setprio 0
	s_barrier
	s_add_i32 s15, s15, 2
	s_add_u32 s44, s44, 0x100
	s_addc_u32 s45, s45, 0
	s_add_u32 s13, s13, 0x100
	s_addc_u32 s14, s14, 0
	s_cmp_gt_u32 s15, 13
	s_cbranch_scc0 .LBB0_98
	s_lshl_b32 s5, s42, 8
	s_and_b64 vcc, exec, s[2:3]
	s_cbranch_vccz .LBB0_101
	v_or_b32_e32 v148, s5, v152
	v_ashrrev_i32_e32 v149, 31, v148
	v_readlane_b32 s10, v255, 11
	v_lshlrev_b64 v[148:149], 6, v[148:149]
	v_readlane_b32 s11, v255, 12
	s_nop 1
	v_lshl_add_u64 v[148:149], s[10:11], 0, v[148:149]
	global_load_dwordx4 v[156:159], v[148:149], off
	global_load_dwordx4 v[160:163], v[148:149], off offset:32
	global_load_dwordx4 v[164:167], v[148:149], off offset:16
	global_load_dwordx4 v[168:171], v[148:149], off offset:48
	s_barrier
.LBB0_101:
	s_andn2_b64 vcc, exec, s[2:3]
	s_cbranch_vccnz .LBB0_103
	s_waitcnt vmcnt(0)
	v_mov_b32_e32 v148, v156
	v_mov_b32_e32 v149, v160
	v_mov_b32_e32 v160, v157
	v_mov_b32_e32 v156, v158
	v_mov_b32_e32 v157, v162
	v_mov_b32_e32 v162, v159
	v_mov_b32_e32 v158, v164
	v_mov_b32_e32 v159, v168
	v_mov_b32_e32 v168, v165
	v_mov_b32_e32 v164, v166
	v_mov_b32_e32 v165, v170
	v_mov_b32_e32 v170, v167
	v_pk_add_f32 v[148:149], v[148:149], v[160:161]
	v_pk_add_f32 v[156:157], v[156:157], v[162:163]
	v_pk_add_f32 v[158:159], v[158:159], v[168:169]
	v_pk_add_f32 v[160:161], v[164:165], v[170:171]
	v_pk_add_f32 v[148:149], v[148:149], v[156:157]
	v_pk_add_f32 v[156:157], v[158:159], v[160:161]
	s_nop 0
	v_pk_add_f32 v[148:149], v[148:149], v[156:157]
	s_nop 0
	v_add_f32_e32 v148, v148, v149
	v_fmamk_f32 v148, v148, 0x3a800000, v191
	v_mul_f32_e32 v149, 0x4b800000, v148
	v_cmp_gt_f32_e32 vcc, s71, v148
	s_nop 1
	v_cndmask_b32_e32 v148, v148, v149, vcc
	v_rsq_f32_e32 v148, v148
	s_nop 0
	v_mul_f32_e32 v149, 0x45800000, v148
	v_cndmask_b32_e32 v148, v148, v149, vcc
	ds_write_b32 v153, v148

.LBB0_928:
	s_add_u32 s18, s40, 0xfffc0080
	s_addc_u32 s19, s41, -1
	s_add_i32 s52, 0, 0x10000
	s_cmp_eq_u32 s51, 12
	s_cselect_b32 s25, s7, s19
	s_cselect_b32 s24, s13, s18
	s_cselect_b32 s23, s5, s43
	s_cselect_b32 s22, s17, s42
	s_add_i32 s53, 0, 0x14000
	v_add_u32_e32 v166, s52, v152
	v_add_u32_e32 v182, s53, v152
	ds_read_b128 v[148:151], v166
	ds_read_b128 v[158:161], v166 offset:1024
	ds_read_b128 v[162:165], v166 offset:2048
	ds_read_b128 v[166:169], v166 offset:3072
	ds_read_b128 v[170:173], v182
	ds_read_b128 v[174:177], v182 offset:1024
	ds_read_b128 v[178:181], v182 offset:2048
	ds_read_b128 v[182:185], v182 offset:3072
	v_lshl_add_u64 v[236:237], s[40:41], 0, v[144:145]
	s_add_i32 m0, s29, 0xc000
	ds_read_b128 v[186:189], v157
	ds_read_b128 v[208:211], v157 offset:1024
	ds_read_b128 v[212:215], v157 offset:2048
	ds_read_b128 v[216:219], v157 offset:3072
	ds_read_b128 v[220:223], v157 offset:4096
	ds_read_b128 v[224:227], v157 offset:5120
	ds_read_b128 v[228:231], v157 offset:6144
	ds_read_b128 v[232:235], v157 offset:7168
	global_load_lds_dwordx4 v[236:237], off
	v_lshl_add_u64 v[236:237], s[40:41], 0, v[146:147]
	s_add_i32 m0, s29, 0xe000
	s_nop 0
	global_load_lds_dwordx4 v[236:237], off
	s_waitcnt vmcnt(8)
	s_waitcnt lgkmcnt(0)
	s_barrier
	s_setprio 1
	s_waitcnt lgkmcnt(0)
	v_mfma_f32_16x16x32_bf16 v[128:131], v[148:151], v[186:189], v[128:131]
	v_mfma_f32_16x16x32_bf16 v[124:127], v[162:165], v[186:189], v[124:127]
	v_mfma_f32_16x16x32_bf16 v[116:119], v[148:151], v[212:215], v[116:119]
	v_mfma_f32_16x16x32_bf16 v[108:111], v[162:165], v[212:215], v[108:111]
	v_mfma_f32_16x16x32_bf16 v[100:103], v[148:151], v[220:223], v[100:103]
	v_mfma_f32_16x16x32_bf16 v[92:95], v[162:165], v[220:223], v[92:95]
	v_mfma_f32_16x16x32_bf16 v[84:87], v[148:151], v[228:231], v[84:87]
	v_mfma_f32_16x16x32_bf16 v[76:79], v[162:165], v[228:231], v[76:79]
	v_mfma_f32_16x16x32_bf16 v[128:131], v[158:161], v[208:211], v[128:131]
	v_mfma_f32_16x16x32_bf16 v[124:127], v[166:169], v[208:211], v[124:127]
	v_mfma_f32_16x16x32_bf16 v[116:119], v[158:161], v[216:219], v[116:119]
	v_mfma_f32_16x16x32_bf16 v[108:111], v[166:169], v[216:219], v[108:111]
	v_mfma_f32_16x16x32_bf16 v[100:103], v[158:161], v[224:227], v[100:103]
	v_mfma_f32_16x16x32_bf16 v[92:95], v[166:169], v[224:227], v[92:95]
	v_mfma_f32_16x16x32_bf16 v[84:87], v[158:161], v[232:235], v[84:87]
	v_mfma_f32_16x16x32_bf16 v[76:79], v[166:169], v[232:235], v[76:79]
	s_setprio 0
	s_setprio 1
	v_mfma_f32_16x16x32_bf16 v[120:123], v[170:173], v[186:189], v[120:123]
	v_mfma_f32_16x16x32_bf16 v[112:115], v[178:181], v[186:189], v[112:115]
	v_mfma_f32_16x16x32_bf16 v[104:107], v[170:173], v[212:215], v[104:107]
	v_mfma_f32_16x16x32_bf16 v[96:99], v[178:181], v[212:215], v[96:99]
	v_mfma_f32_16x16x32_bf16 v[88:91], v[170:173], v[220:223], v[88:91]
	v_mfma_f32_16x16x32_bf16 v[80:83], v[178:181], v[220:223], v[80:83]
	v_mfma_f32_16x16x32_bf16 v[72:75], v[170:173], v[228:231], v[72:75]
	v_mfma_f32_16x16x32_bf16 v[68:71], v[178:181], v[228:231], v[68:71]
	v_mfma_f32_16x16x32_bf16 v[120:123], v[174:177], v[208:211], v[120:123]
	v_mfma_f32_16x16x32_bf16 v[112:115], v[182:185], v[208:211], v[112:115]
	v_mfma_f32_16x16x32_bf16 v[104:107], v[174:177], v[216:219], v[104:107]
	v_mfma_f32_16x16x32_bf16 v[96:99], v[182:185], v[216:219], v[96:99]
	v_mfma_f32_16x16x32_bf16 v[88:91], v[174:177], v[224:227], v[88:91]
	v_mfma_f32_16x16x32_bf16 v[80:83], v[182:185], v[224:227], v[80:83]
	v_mfma_f32_16x16x32_bf16 v[72:75], v[174:177], v[232:235], v[72:75]
	v_mfma_f32_16x16x32_bf16 v[68:71], v[182:185], v[232:235], v[68:71]
	s_setprio 0
	s_barrier
	s_add_i32 s18, s52, s28
	v_lshl_add_u64 v[236:237], s[22:23], 0, v[2:3]
	s_mov_b32 m0, s18
	ds_read_b128 v[186:189], v157 offset:16384
	ds_read_b128 v[208:211], v157 offset:17408
	ds_read_b128 v[212:215], v157 offset:18432
	ds_read_b128 v[216:219], v157 offset:19456
	ds_read_b128 v[220:223], v157 offset:20480
	ds_read_b128 v[224:227], v157 offset:21504
	ds_read_b128 v[228:231], v157 offset:22528
	ds_read_b128 v[232:235], v157 offset:23552
	global_load_lds_dwordx4 v[236:237], off
	s_add_i32 m0, s18, 0x2000
	s_add_u32 s18, s22, 0x40000
	v_lshl_add_u64 v[238:239], s[22:23], 0, v[142:143]
	s_addc_u32 s19, s23, 0
	s_add_i32 s52, s53, s28
	global_load_lds_dwordx4 v[238:239], off
	v_lshl_add_u64 v[240:241], s[18:19], 0, v[2:3]
	s_mov_b32 m0, s52
	v_lshl_add_u64 v[242:243], s[24:25], 0, v[140:141]
	global_load_lds_dwordx4 v[240:241], off
	v_lshl_add_u64 v[240:241], s[18:19], 0, v[142:143]
	s_add_i32 m0, s52, 0x2000
	s_nop 0
	global_load_lds_dwordx4 v[240:241], off
	v_lshl_add_u64 v[240:241], s[24:25], 0, v[0:1]
	s_mov_b32 m0, s29
	s_nop 0
	global_load_lds_dwordx4 v[240:241], off
	s_mov_b32 m0, s44
	s_nop 0
	global_load_lds_dwordx4 v[242:243], off
	s_waitcnt vmcnt(8)
	s_waitcnt lgkmcnt(0)
	s_barrier
	s_setprio 1
	s_waitcnt lgkmcnt(0)
	v_mfma_f32_16x16x32_bf16 v[64:67], v[148:151], v[186:189], v[64:67]
	v_mfma_f32_16x16x32_bf16 v[60:63], v[162:165], v[186:189], v[60:63]
	v_mfma_f32_16x16x32_bf16 v[52:55], v[148:151], v[212:215], v[52:55]
	v_mfma_f32_16x16x32_bf16 v[44:47], v[162:165], v[212:215], v[44:47]
	v_mfma_f32_16x16x32_bf16 v[36:39], v[148:151], v[220:223], v[36:39]
	v_mfma_f32_16x16x32_bf16 v[28:31], v[162:165], v[220:223], v[28:31]
	v_mfma_f32_16x16x32_bf16 v[20:23], v[148:151], v[228:231], v[20:23]
	v_mfma_f32_16x16x32_bf16 v[12:15], v[162:165], v[228:231], v[12:15]
	v_mfma_f32_16x16x32_bf16 v[64:67], v[158:161], v[208:211], v[64:67]
	v_mfma_f32_16x16x32_bf16 v[60:63], v[166:169], v[208:211], v[60:63]
	v_mfma_f32_16x16x32_bf16 v[52:55], v[158:161], v[216:219], v[52:55]
	v_mfma_f32_16x16x32_bf16 v[44:47], v[166:169], v[216:219], v[44:47]
	v_mfma_f32_16x16x32_bf16 v[36:39], v[158:161], v[224:227], v[36:39]
	v_mfma_f32_16x16x32_bf16 v[28:31], v[166:169], v[224:227], v[28:31]
	v_mfma_f32_16x16x32_bf16 v[20:23], v[158:161], v[232:235], v[20:23]
	v_mfma_f32_16x16x32_bf16 v[12:15], v[166:169], v[232:235], v[12:15]
	s_setprio 0
	s_setprio 1
	v_mfma_f32_16x16x32_bf16 v[56:59], v[170:173], v[186:189], v[56:59]
	v_mfma_f32_16x16x32_bf16 v[48:51], v[178:181], v[186:189], v[48:51]
	v_mfma_f32_16x16x32_bf16 v[40:43], v[170:173], v[212:215], v[40:43]
	v_mfma_f32_16x16x32_bf16 v[32:35], v[178:181], v[212:215], v[32:35]
	v_mfma_f32_16x16x32_bf16 v[24:27], v[170:173], v[220:223], v[24:27]
	v_mfma_f32_16x16x32_bf16 v[16:19], v[178:181], v[220:223], v[16:19]
	v_mfma_f32_16x16x32_bf16 v[8:11], v[170:173], v[228:231], v[8:11]
	v_mfma_f32_16x16x32_bf16 v[4:7], v[178:181], v[228:231], v[4:7]
	v_mfma_f32_16x16x32_bf16 v[56:59], v[174:177], v[208:211], v[56:59]
	v_mfma_f32_16x16x32_bf16 v[48:51], v[182:185], v[208:211], v[48:51]
	v_mfma_f32_16x16x32_bf16 v[40:43], v[174:177], v[216:219], v[40:43]
	v_mfma_f32_16x16x32_bf16 v[32:35], v[182:185], v[216:219], v[32:35]
	v_mfma_f32_16x16x32_bf16 v[24:27], v[174:177], v[224:227], v[24:27]
	v_mfma_f32_16x16x32_bf16 v[16:19], v[182:185], v[224:227], v[16:19]
	v_mfma_f32_16x16x32_bf16 v[8:11], v[174:177], v[232:235], v[8:11]
	v_mfma_f32_16x16x32_bf16 v[4:7], v[182:185], v[232:235], v[4:7]
	s_setprio 0
	s_barrier
	s_add_i32 s52, 0, 0x18000
	s_add_i32 s53, 0, 0x1c000
	v_add_u32_e32 v166, s52, v152
	v_add_u32_e32 v182, s53, v152
	ds_read_b128 v[148:151], v166
	ds_read_b128 v[158:161], v166 offset:1024
	ds_read_b128 v[162:165], v166 offset:2048
	ds_read_b128 v[166:169], v166 offset:3072
	ds_read_b128 v[170:173], v182
	ds_read_b128 v[174:177], v182 offset:1024
	ds_read_b128 v[178:181], v182 offset:2048
	ds_read_b128 v[182:185], v182 offset:3072
	s_add_u32 s18, s24, 0x40000
	s_addc_u32 s19, s25, 0
	s_mov_b32 m0, s45
	v_lshl_add_u64 v[244:245], s[18:19], 0, v[0:1]
	ds_read_b128 v[186:189], v157 offset:32768
	ds_read_b128 v[208:211], v157 offset:33792
	ds_read_b128 v[212:215], v157 offset:34816
	ds_read_b128 v[216:219], v157 offset:35840
	ds_read_b128 v[220:223], v157 offset:36864
	ds_read_b128 v[224:227], v157 offset:37888
	ds_read_b128 v[228:231], v157 offset:38912
	ds_read_b128 v[232:235], v157 offset:39936
	global_load_lds_dwordx4 v[244:245], off
	v_lshl_add_u64 v[244:245], s[18:19], 0, v[140:141]
	s_mov_b32 m0, s46
	s_nop 0
	global_load_lds_dwordx4 v[244:245], off
	s_waitcnt vmcnt(8)
	s_waitcnt lgkmcnt(0)
	s_barrier
	s_setprio 1
	s_waitcnt lgkmcnt(0)
	v_mfma_f32_16x16x32_bf16 v[128:131], v[148:151], v[186:189], v[128:131]
	v_mfma_f32_16x16x32_bf16 v[124:127], v[162:165], v[186:189], v[124:127]
	v_mfma_f32_16x16x32_bf16 v[116:119], v[148:151], v[212:215], v[116:119]
	v_mfma_f32_16x16x32_bf16 v[108:111], v[162:165], v[212:215], v[108:111]
	v_mfma_f32_16x16x32_bf16 v[100:103], v[148:151], v[220:223], v[100:103]
	v_mfma_f32_16x16x32_bf16 v[92:95], v[162:165], v[220:223], v[92:95]
	v_mfma_f32_16x16x32_bf16 v[84:87], v[148:151], v[228:231], v[84:87]
	v_mfma_f32_16x16x32_bf16 v[76:79], v[162:165], v[228:231], v[76:79]
	v_mfma_f32_16x16x32_bf16 v[128:131], v[158:161], v[208:211], v[128:131]
	v_mfma_f32_16x16x32_bf16 v[124:127], v[166:169], v[208:211], v[124:127]
	v_mfma_f32_16x16x32_bf16 v[116:119], v[158:161], v[216:219], v[116:119]
	v_mfma_f32_16x16x32_bf16 v[108:111], v[166:169], v[216:219], v[108:111]
	v_mfma_f32_16x16x32_bf16 v[100:103], v[158:161], v[224:227], v[100:103]
	v_mfma_f32_16x16x32_bf16 v[92:95], v[166:169], v[224:227], v[92:95]
	v_mfma_f32_16x16x32_bf16 v[84:87], v[158:161], v[232:235], v[84:87]
	v_mfma_f32_16x16x32_bf16 v[76:79], v[166:169], v[232:235], v[76:79]
	s_setprio 0
	s_setprio 1
	v_mfma_f32_16x16x32_bf16 v[120:123], v[170:173], v[186:189], v[120:123]
	v_mfma_f32_16x16x32_bf16 v[112:115], v[178:181], v[186:189], v[112:115]
	v_mfma_f32_16x16x32_bf16 v[104:107], v[170:173], v[212:215], v[104:107]
	v_mfma_f32_16x16x32_bf16 v[96:99], v[178:181], v[212:215], v[96:99]
	v_mfma_f32_16x16x32_bf16 v[88:91], v[170:173], v[220:223], v[88:91]
	v_mfma_f32_16x16x32_bf16 v[80:83], v[178:181], v[220:223], v[80:83]
	v_mfma_f32_16x16x32_bf16 v[72:75], v[170:173], v[228:231], v[72:75]
	v_mfma_f32_16x16x32_bf16 v[68:71], v[178:181], v[228:231], v[68:71]
	v_mfma_f32_16x16x32_bf16 v[120:123], v[174:177], v[208:211], v[120:123]
	v_mfma_f32_16x16x32_bf16 v[112:115], v[182:185], v[208:211], v[112:115]
	v_mfma_f32_16x16x32_bf16 v[104:107], v[174:177], v[216:219], v[104:107]
	v_mfma_f32_16x16x32_bf16 v[96:99], v[182:185], v[216:219], v[96:99]
	v_mfma_f32_16x16x32_bf16 v[88:91], v[174:177], v[224:227], v[88:91]
	v_mfma_f32_16x16x32_bf16 v[80:83], v[182:185], v[224:227], v[80:83]
	v_mfma_f32_16x16x32_bf16 v[72:75], v[174:177], v[232:235], v[72:75]
	v_mfma_f32_16x16x32_bf16 v[68:71], v[182:185], v[232:235], v[68:71]
	s_setprio 0
	s_barrier
	s_add_i32 s18, s52, s28
	v_lshl_add_u64 v[236:237], v[236:237], 0, s[92:93]
	s_mov_b32 m0, s18
	ds_read_b128 v[186:189], v157 offset:49152
	ds_read_b128 v[208:211], v157 offset:50176
	ds_read_b128 v[212:215], v157 offset:51200
	ds_read_b128 v[216:219], v157 offset:52224
	ds_read_b128 v[220:223], v157 offset:53248
	ds_read_b128 v[224:227], v157 offset:54272
	ds_read_b128 v[228:231], v157 offset:55296
	ds_read_b128 v[232:235], v157 offset:56320
	global_load_lds_dwordx4 v[236:237], off
	s_add_i32 m0, s18, 0x2000
	s_add_u32 s18, s22, 0x40080
	v_lshl_add_u64 v[236:237], v[238:239], 0, s[92:93]
	s_addc_u32 s19, s23, 0
	s_add_i32 s22, s53, s28
	global_load_lds_dwordx4 v[236:237], off
	v_lshl_add_u64 v[236:237], s[18:19], 0, v[2:3]
	s_mov_b32 m0, s22
	s_nop 0
	global_load_lds_dwordx4 v[236:237], off
	v_lshl_add_u64 v[236:237], s[18:19], 0, v[142:143]
	s_add_i32 m0, s22, 0x2000
	s_nop 0
	global_load_lds_dwordx4 v[236:237], off
	v_lshl_add_u64 v[236:237], v[240:241], 0, s[92:93]
	s_mov_b32 m0, s47
	s_nop 0
	global_load_lds_dwordx4 v[236:237], off
	v_lshl_add_u64 v[236:237], v[242:243], 0, s[92:93]
	s_mov_b32 m0, s48
	s_nop 0
	global_load_lds_dwordx4 v[236:237], off
	s_waitcnt vmcnt(8)
	s_waitcnt lgkmcnt(0)
	s_barrier
	s_setprio 1
	s_waitcnt lgkmcnt(0)
	v_mfma_f32_16x16x32_bf16 v[64:67], v[148:151], v[186:189], v[64:67]
	v_mfma_f32_16x16x32_bf16 v[60:63], v[162:165], v[186:189], v[60:63]
	v_mfma_f32_16x16x32_bf16 v[52:55], v[148:151], v[212:215], v[52:55]
	v_mfma_f32_16x16x32_bf16 v[44:47], v[162:165], v[212:215], v[44:47]
	v_mfma_f32_16x16x32_bf16 v[36:39], v[148:151], v[220:223], v[36:39]
	v_mfma_f32_16x16x32_bf16 v[28:31], v[162:165], v[220:223], v[28:31]
	v_mfma_f32_16x16x32_bf16 v[20:23], v[148:151], v[228:231], v[20:23]
	v_mfma_f32_16x16x32_bf16 v[12:15], v[162:165], v[228:231], v[12:15]
	v_mfma_f32_16x16x32_bf16 v[64:67], v[158:161], v[208:211], v[64:67]
	v_mfma_f32_16x16x32_bf16 v[60:63], v[166:169], v[208:211], v[60:63]
	v_mfma_f32_16x16x32_bf16 v[52:55], v[158:161], v[216:219], v[52:55]
	v_mfma_f32_16x16x32_bf16 v[44:47], v[166:169], v[216:219], v[44:47]
	v_mfma_f32_16x16x32_bf16 v[36:39], v[158:161], v[224:227], v[36:39]
	v_mfma_f32_16x16x32_bf16 v[28:31], v[166:169], v[224:227], v[28:31]
	v_mfma_f32_16x16x32_bf16 v[20:23], v[158:161], v[232:235], v[20:23]
	v_mfma_f32_16x16x32_bf16 v[12:15], v[166:169], v[232:235], v[12:15]
	s_setprio 0
	s_setprio 1
	v_mfma_f32_16x16x32_bf16 v[56:59], v[170:173], v[186:189], v[56:59]
	v_mfma_f32_16x16x32_bf16 v[48:51], v[178:181], v[186:189], v[48:51]
	v_mfma_f32_16x16x32_bf16 v[40:43], v[170:173], v[212:215], v[40:43]
	v_mfma_f32_16x16x32_bf16 v[32:35], v[178:181], v[212:215], v[32:35]
	v_mfma_f32_16x16x32_bf16 v[24:27], v[170:173], v[220:223], v[24:27]
	v_mfma_f32_16x16x32_bf16 v[16:19], v[178:181], v[220:223], v[16:19]
	v_mfma_f32_16x16x32_bf16 v[8:11], v[170:173], v[228:231], v[8:11]
	v_mfma_f32_16x16x32_bf16 v[4:7], v[178:181], v[228:231], v[4:7]
	v_mfma_f32_16x16x32_bf16 v[56:59], v[174:177], v[208:211], v[56:59]
	v_mfma_f32_16x16x32_bf16 v[48:51], v[182:185], v[208:211], v[48:51]
	v_mfma_f32_16x16x32_bf16 v[40:43], v[174:177], v[216:219], v[40:43]
	v_mfma_f32_16x16x32_bf16 v[32:35], v[182:185], v[216:219], v[32:35]
	v_mfma_f32_16x16x32_bf16 v[24:27], v[174:177], v[224:227], v[24:27]
	v_mfma_f32_16x16x32_bf16 v[16:19], v[182:185], v[224:227], v[16:19]
	v_mfma_f32_16x16x32_bf16 v[8:11], v[174:177], v[232:235], v[8:11]
	v_mfma_f32_16x16x32_bf16 v[4:7], v[182:185], v[232:235], v[4:7]
	s_setprio 0
	s_barrier
	s_add_i32 s51, s51, 2
	s_add_u32 s40, s40, 0x100
	s_addc_u32 s41, s41, 0
	s_add_u32 s42, s42, 0x100
	s_addc_u32 s43, s43, 0
	s_cmp_gt_u32 s51, 13
	s_cbranch_scc0 .LBB0_928
	s_lshl_b32 s5, s16, 8
	s_and_b64 vcc, exec, s[2:3]
	s_cbranch_vccz .LBB0_931
	v_or_b32_e32 v148, s5, v154
	v_ashrrev_i32_e32 v149, 31, v148
	v_lshlrev_b64 v[148:149], 6, v[148:149]
	v_lshl_add_u64 v[166:167], s[74:75], 0, v[148:149]
	global_load_dwordx4 v[148:151], v[166:167], off
	global_load_dwordx4 v[158:161], v[166:167], off offset:32
	global_load_dwordx4 v[162:165], v[166:167], off offset:16
	s_nop 0
	global_load_dwordx4 v[166:169], v[166:167], off offset:48
	s_barrier
.LBB0_931:
	s_andn2_b64 vcc, exec, s[2:3]
	s_cbranch_vccnz .LBB0_933
	s_waitcnt vmcnt(0)
	v_mov_b32_e32 v170, v148
	v_mov_b32_e32 v171, v158
	v_mov_b32_e32 v158, v149
	v_mov_b32_e32 v148, v150
	v_mov_b32_e32 v149, v160
	v_mov_b32_e32 v160, v151
	v_mov_b32_e32 v150, v162
	v_mov_b32_e32 v151, v166
	v_mov_b32_e32 v166, v163
	v_mov_b32_e32 v162, v164
	v_mov_b32_e32 v163, v168
	v_mov_b32_e32 v168, v165
	v_pk_add_f32 v[158:159], v[170:171], v[158:159]
	v_pk_add_f32 v[148:149], v[148:149], v[160:161]
	v_pk_add_f32 v[150:151], v[150:151], v[166:167]
	v_pk_add_f32 v[160:161], v[162:163], v[168:169]
	v_pk_add_f32 v[148:149], v[158:159], v[148:149]
	v_pk_add_f32 v[150:151], v[150:151], v[160:161]
	s_nop 0
	v_pk_add_f32 v[148:149], v[148:149], v[150:151]
	s_nop 0
	v_add_f32_e32 v148, v148, v149
	v_fmamk_f32 v148, v148, 0x3a800000, v191
	v_mul_f32_e32 v149, 0x4b800000, v148
	v_cmp_gt_f32_e32 vcc, s71, v148
	s_nop 1
	v_cndmask_b32_e32 v148, v148, v149, vcc
	v_rsq_f32_e32 v148, v148
	s_nop 0
	v_mul_f32_e32 v149, 0x45800000, v148
	v_cndmask_b32_e32 v148, v148, v149, vcc
	ds_write_b32 v155, v148
